# B far loop: waves 4-7 take the step barrier half a step away from waves 0-3 (4-slot ring)
# speedup vs baseline: 1.0017x; 1.0017x over previous
; #define LAS __attribute__((address_space(3)))
; #define WAITBAR2() asm volatile("s_waitcnt vmcnt(2) lgkmcnt(0)\n\ts_barrier" ::: "memory")
; #define ISSUE_UP() do { STG_ISSUE(s_iss < sb_end ? s_iss : sb_end, slot_i); ++s_iss; slot_i = slot_i == NSTG - 1 ? 0 : slot_i + 1; } while (0)
; __device__ __forceinline__ void blk_B(int b, int hd, int chunk, const bf16_t* QK, const bf16_t* VT, bf16_t* mixed, LAS unsigned char* lds, const float* tblg, float wfar, float lam, float osc, const float* subln, int tid, int lane, int wave) {
;     const int q = lane & 31, h = lane >> 5, qb = chunk * 8 + wave;
;     LOAD_HEAD_TABLE(8 + hd);
;     const size_t tok0 = (size_t)b * SEQ;
;     const bf16_t* Qp = QK + (tok0 + qb * 32 + q) * 2048 + 1024 + hd * 64 + 8 * h;
;     bf16x8 qf[4];
; #pragma unroll
;     for (int s = 0; s < 4; ++s) qf[s] = *(const bf16x8*)(Qp + 16 * s);
;     const Stage st = make_stage(tid, QK, VT, tok0, 1280 + hd * 64, 512 + hd * 64);
;     LAS unsigned char* sb = lds + SBUF_OFF;
;     const int sb_end = chunk * 4 + 3;
;     int s_iss = 0, slot_i = 0, slot_c = 0;
;     ISSUE_UP(); ISSUE_UP();
;     WAITBAR2();
;     f32x16 oa0 = {}, oa1 = {}, ob0 = {}, ob1 = {}; float la = 0.f, lb = 0.f; bool scaled = false;
;     const LAS unsigned char* tb = LANE_TBL();
.LBB0_353:
	s_or_b64 exec, exec, s[0:1]
	s_ashr_i32 s18, s28, 5
	s_sub_i32 s19, 31, s18
	s_lshl_b32 s29, s19, 3
	s_add_i32 s29, s29, s25
	s_lshl_b32 s0, s28, 11
	s_and_b32 s30, s0, 0xe000
	s_lshl_b32 s0, s29, 5
	s_ashr_i32 s1, s0, 31
	s_add_u32 s0, s0, s30
	s_addc_u32 s1, s1, 0
	v_mov_b32_e32 v195, s1
	v_or_b32_e32 v194, s0, v172
	s_waitcnt vmcnt(0)
	v_lshlrev_b64 v[2:3], 12, v[194:195]
	s_lshl_b32 s28, s27, 6
	s_lshl_b32 s92, s27, 7
	v_readfirstlane_b32 s27, v170
	v_lshl_add_u64 v[2:3], s[80:81], 0, v[2:3]
	s_ashr_i32 s34, s27, 8
	v_lshl_add_u64 v[2:3], v[2:3], 0, s[92:93]
	v_lshlrev_b32_e32 v0, 1, v174
	s_lshl_b32 s0, s34, 5
	v_lshl_add_u64 v[2:3], v[2:3], 0, v[0:1]
	s_ashr_i32 s1, s0, 31
	v_or_b32_e32 v0, s30, v177
	global_load_dwordx4 v[130:133], v[2:3], off offset:2048
	global_load_dwordx4 v[134:137], v[2:3], off offset:2080
	global_load_dwordx4 v[138:141], v[2:3], off offset:2112
	global_load_dwordx4 v[142:145], v[2:3], off offset:2144
	s_ashr_i32 s31, s27, 6
	v_lshl_add_u64 v[2:3], s[0:1], 0, v[0:1]
	s_lshr_b32 s27, s27, 2
	v_lshlrev_b64 v[2:3], 12, v[2:3]
	v_and_or_b32 v4, s27, 32, v172
	v_lshl_add_u64 v[2:3], s[80:81], 0, v[2:3]
	s_and_b32 s35, s31, 3
	v_or_b32_e32 v4, s28, v4
	v_lshl_add_u64 v[2:3], v[2:3], 0, s[92:93]
	s_lshl_b32 s92, s35, 5
	v_lshlrev_b32_e32 v4, 17, v4
	v_mov_b32_e32 v5, v1
	v_lshl_add_u64 v[2:3], v[2:3], 0, s[92:93]
	v_lshl_add_u64 v[4:5], s[4:5], 0, v[4:5]
	s_lshl_b32 s92, s30, 1
	v_lshl_add_u64 v[4:5], v[4:5], 0, s[92:93]
	s_lshl_b32 s34, s34, 13
	s_lshl_b32 s35, s35, 10
	v_lshl_add_u64 v[4:5], s[0:1], 1, v[4:5]
	s_lshl_b32 s0, s31, 5
	v_lshlrev_b32_e32 v0, 1, v176
	s_or_b32 s34, s35, s34
	s_and_b32 s92, s0, 32
	v_lshl_add_u64 v[196:197], v[2:3], 0, v[0:1]
	v_lshl_add_u64 v[4:5], v[4:5], 0, s[92:93]
	s_add_i32 s76, s34, 0
	v_lshl_add_u64 v[2:3], v[196:197], 0, s[14:15]
	v_lshl_add_u64 v[4:5], v[4:5], 0, v[0:1]
	s_mov_b64 s[0:1], 0x4000000
	s_add_i32 m0, s76, 0x8900
	v_lshl_add_u64 v[198:199], v[4:5], 0, s[0:1]
	global_load_lds_dwordx4 v[2:3], off
	s_add_i32 m0, s76, 0x9900
	s_mov_b64 s[0:1], 0x40a00
	global_load_lds_dwordx4 v[198:199], off
	v_lshl_add_u64 v[2:3], v[196:197], 0, s[0:1]
	s_add_i32 m0, s76, 0xc900
	s_mov_b64 s[0:1], 0x4000080
	global_load_lds_dwordx4 v[2:3], off
	v_lshl_add_u64 v[2:3], v[4:5], 0, s[0:1]
	s_add_i32 m0, s76, 0xd900
	s_lshl_b32 s0, s19, 2
	global_load_lds_dwordx4 v[2:3], off
	s_waitcnt vmcnt(2) lgkmcnt(0)
	s_barrier
	v_mov_b32_e32 v16, v1
	v_mov_b32_e32 v17, v1
	s_or_b32 s78, s0, 3
	s_lshl_b32 s0, s18, 2
	v_mov_b32_e32 v0, v1
	v_mov_b32_e32 v2, v1
	v_mov_b32_e32 v3, v1
	v_mov_b32_e32 v4, v1
	v_mov_b32_e32 v5, v1
	v_mov_b32_e32 v6, v1
	v_mov_b32_e32 v7, v1
	v_mov_b32_e32 v8, v1
	v_mov_b32_e32 v9, v1
	v_mov_b32_e32 v10, v1
	v_mov_b32_e32 v11, v1
	v_mov_b32_e32 v12, v1
	v_mov_b32_e32 v13, v1
	v_mov_b32_e32 v14, v1
	v_mov_b32_e32 v15, v1
	v_mov_b64_e32 v[32:33], v[16:17]
	v_mov_b64_e32 v[64:65], v[16:17]
	v_mov_b64_e32 v[48:49], v[16:17]
	s_mov_b32 s77, 2
	s_mov_b32 s55, s54
	s_mov_b32 s56, s54
	s_mov_b32 s57, s54
	s_mov_b32 s58, s54
	s_mov_b32 s59, s54
	s_mov_b32 s60, s54
	s_mov_b32 s61, s54
	s_mov_b32 s62, s54
	s_mov_b32 s63, s54
	s_mov_b32 s64, s54
	s_mov_b32 s65, s54
	s_mov_b32 s66, s54
	s_mov_b32 s67, s54
	s_mov_b32 s68, s54
	s_mov_b32 s69, s54
	s_mov_b32 s70, s54
	s_mov_b32 s71, s54
	s_mov_b32 s79, 0
	s_sub_i32 s82, 0, s0
	v_lshl_add_u32 v206, s18, 10, v205
	s_mov_b64 s[18:19], 0
	s_movk_i32 s83, 0xff80
	s_mov_b32 s30, s29
	s_mov_b32 s31, 0
	v_mov_b64_e32 v[30:31], v[14:15]
	v_mov_b64_e32 v[28:29], v[12:13]
	v_mov_b64_e32 v[26:27], v[10:11]
	v_mov_b64_e32 v[24:25], v[8:9]
	v_mov_b64_e32 v[22:23], v[6:7]
	v_mov_b64_e32 v[20:21], v[4:5]
	v_mov_b64_e32 v[18:19], v[2:3]
	v_mov_b64_e32 v[62:63], v[14:15]
	v_mov_b64_e32 v[60:61], v[12:13]
	v_mov_b64_e32 v[58:59], v[10:11]
	v_mov_b64_e32 v[56:57], v[8:9]
	v_mov_b64_e32 v[54:55], v[6:7]
	v_mov_b64_e32 v[52:53], v[4:5]
	v_mov_b64_e32 v[50:51], v[2:3]
	v_mov_b64_e32 v[46:47], v[14:15]
	v_mov_b64_e32 v[44:45], v[12:13]
	v_mov_b64_e32 v[42:43], v[10:11]
	v_mov_b64_e32 v[40:41], v[8:9]
	v_mov_b64_e32 v[38:39], v[6:7]
	v_mov_b64_e32 v[36:37], v[4:5]
	v_mov_b64_e32 v[34:35], v[2:3]
	v_mov_b64_e32 v[200:201], v[0:1]
	s_waitcnt vmcnt(0)
	s_branch .LBB0_356

; #define LAS __attribute__((address_space(3)))
; __device__ __forceinline__ void step_B(const bool FAR, const LAS unsigned char* cb, const LAS unsigned char* tp0, const LAS unsigned char* tp1, const bf16x8 (&qf)[4],
;                                        f32x16& oa0, f32x16& oa1, f32x16& ob0, f32x16& ob1, float& la, float& lb) {
;     bf16x8 kfA[4], vfA[2][2], kfB[4], vfB[2][2]; f32x16 tA, tB;
;     LOADK(kfA, cb); if (!FAR) LOADT(tA, tp0); LOADV(vfA, cb);
;     SCHED_FENCE();
;     f32x16 S0, S1;
;     if (FAR) { S0 = mfma32(kfA[0], qf[0], f32x16{}); S1 = mfma32(kfA[2], qf[2], f32x16{}); }
;     else { S0 = mfma32(kfA[0], qf[0], tA); S1 = mfma32(kfA[2], qf[2], tA); }
;     S0 = mfma32(kfA[1], qf[1], S0); S1 = mfma32(kfA[3], qf[3], S1);
;     kfB[0] = *(const LAS bf16x8*)(cb + 8192); kfB[1] = *(const LAS bf16x8*)(cb + 8192 + 1024); if (!FAR) LOADT(tB, tp1);
;     SCHED_FENCE();
;     bf16x8 p0, p1, r0, r1;
;     f32x16 S2; if (FAR) S2 = mfma32(kfB[0], qf[0], f32x16{}); else S2 = mfma32(kfB[0], qf[0], tB);
;     EXP4(S0, 0); EXP4(S0, 4); SCHED_FENCE();
;     S2 = mfma32(kfB[1], qf[1], S2); EXP4(S0, 8); EXP4(S0, 12); SCHED_FENCE();
;     SUM16(S0, la); pack_p(S0, p0, p1); SCHED_FENCE();
;     f32x16 tB2; kfB[2] = *(const LAS bf16x8*)(cb + 8192 + 2048); kfB[3] = *(const LAS bf16x8*)(cb + 8192 + 3072); if (!FAR) LOADT(tB2, tp1);
;     oa0 = mfma32(vfA[0][0], p0, oa0); EXP4(S1, 0); SCHED_FENCE();
;     oa1 = mfma32(vfA[1][0], p0, oa1); EXP4(S1, 4); SCHED_FENCE();
;     oa0 = mfma32(vfA[0][1], p1, oa0); EXP4(S1, 8); SCHED_FENCE();
;     oa1 = mfma32(vfA[1][1], p1, oa1); EXP4(S1, 12); SCHED_FENCE();
;     f32x16 S3; if (FAR) S3 = mfma32(kfB[2], qf[2], f32x16{}); else S3 = mfma32(kfB[2], qf[2], tB2);
;     SUM16(S1, lb); SCHED_FENCE();
;     S3 = mfma32(kfB[3], qf[3], S3); pack_p(S1, r0, r1); SCHED_FENCE();
;     LOADV(vfB, cb + 8192);
;     ob0 = mfma32(vfA[0][0], r0, ob0); EXP4(S2, 0); SCHED_FENCE();
;     ob1 = mfma32(vfA[1][0], r0, ob1); EXP4(S2, 4); SCHED_FENCE();
;     ob0 = mfma32(vfA[0][1], r1, ob0); EXP4(S2, 8); SCHED_FENCE();
;     ob1 = mfma32(vfA[1][1], r1, ob1); EXP4(S2, 12); SCHED_FENCE();
;     SUM16(S2, la); pack_p(S2, p0, p1); SCHED_FENCE();
;     oa0 = mfma32(vfB[0][0], p0, oa0); EXP4(S3, 0); SCHED_FENCE();
;     oa1 = mfma32(vfB[1][0], p0, oa1); EXP4(S3, 4); SCHED_FENCE();
;     oa0 = mfma32(vfB[0][1], p1, oa0); EXP4(S3, 8); SCHED_FENCE();
.LBB0_355:
	s_add_i32 s0, s77, 1
	s_cmp_lg_u32 s77, 3
	s_cselect_b32 s77, s0, 0
	s_add_i32 s0, s31, 1
	s_waitcnt vmcnt(2) lgkmcnt(0)
	s_barrier
	s_cmp_lg_u32 s31, 3
	s_cselect_b32 s31, s0, 0
	s_add_i32 s83, s83, 1
	s_add_i32 s30, s30, -2
	s_add_i32 s79, s79, 2
	s_cmp_lg_u32 s82, s83
	v_add_u32_e32 v206, 0x100, v206
	s_cbranch_scc0 .LBB0_308
.LBB0_356:
	s_add_i32 s0, s83, 0x82
	s_min_u32 s92, s0, s78
	s_lshl_b32 s27, s77, 14
	s_lshl_b64 s[0:1], s[92:93], 18
	v_lshl_add_u64 v[66:67], v[196:197], 0, s[0:1]
	s_add_i32 s0, s76, s27
	v_lshl_add_u64 v[66:67], v[66:67], 0, s[14:15]
	s_add_i32 m0, s0, 0x8900
	s_lshl_b32 s92, s92, 7
	global_load_lds_dwordx4 v[66:67], off
	v_lshl_add_u64 v[66:67], v[198:199], 0, s[92:93]
	s_add_i32 m0, s0, 0x9900
	s_lshl_b32 s27, s31, 14
	global_load_lds_dwordx4 v[66:67], off
	s_cmp_gt_i32 s30, 49
	s_cbranch_scc0 .Lattn_b_slow
	s_cmp_gt_u32 s25, 3
	s_cbranch_scc1 .Lattn_b_lag_entry
	v_add_u32_e32 v0, s27, v179
	ds_read_b128 v[146:149], v0 offset:35072
	ds_read_b128 v[150:153], v0 offset:36096
	ds_read_b128 v[154:157], v0 offset:37120
	ds_read_b128 v[158:161], v0 offset:38144
.Lattn_b_fast_top:
	s_waitcnt lgkmcnt(0)
	v_mfma_f32_32x32x16_bf16 v[66:81], v[146:149], v[130:133], 0
	v_mfma_f32_32x32x16_bf16 v[66:81], v[150:153], v[134:137], v[66:81]
	ds_read_b128 v[162:165], v0 offset:39168
	ds_read_b128 v[166:169], v0 offset:40192
	ds_read_b128 v[208:211], v0 offset:41216
	ds_read_b128 v[212:215], v0 offset:42240
	ds_read_b128 v[146:149], v0 offset:43264
	ds_read_b128 v[150:153], v0 offset:44288
	s_nop 4
	v_mfma_f32_32x32x16_bf16 v[82:97], v[154:157], v[138:141], 0
	v_exp_f32_e32 v66, v66
	v_exp_f32_e32 v67, v67
	v_exp_f32_e32 v68, v68
	v_exp_f32_e32 v69, v69
	v_add_f32_e32 v114, v66, v67
	v_add_f32_e32 v116, v68, v69
	v_add_f32_e32 v114, v114, v116
	v_cvt_pk_bf16_f32 v98, v66, v67
	v_cvt_pk_bf16_f32 v99, v68, v69
	v_mfma_f32_32x32x16_bf16 v[82:97], v[158:161], v[142:145], v[82:97]
	ds_read_b128 v[154:157], v0 offset:45312
	ds_read_b128 v[158:161], v0 offset:46336
	v_exp_f32_e32 v70, v70
	v_exp_f32_e32 v71, v71
	v_exp_f32_e32 v72, v72
	v_exp_f32_e32 v73, v73
	v_add_f32_e32 v115, v70, v71
	v_add_f32_e32 v116, v72, v73
	v_add_f32_e32 v115, v115, v116
	v_add_f32_e32 v114, v114, v115
	v_cvt_pk_bf16_f32 v100, v70, v71
	v_cvt_pk_bf16_f32 v101, v72, v73
	v_exp_f32_e32 v74, v74
	v_exp_f32_e32 v75, v75
	v_exp_f32_e32 v76, v76
	v_exp_f32_e32 v77, v77
	v_add_f32_e32 v115, v74, v75
	v_add_f32_e32 v116, v76, v77
	v_add_f32_e32 v115, v115, v116
	v_add_f32_e32 v114, v114, v115
	v_cvt_pk_bf16_f32 v102, v74, v75
	v_cvt_pk_bf16_f32 v103, v76, v77
	v_exp_f32_e32 v78, v78
	v_exp_f32_e32 v79, v79
	v_exp_f32_e32 v80, v80
	v_exp_f32_e32 v81, v81
	v_add_f32_e32 v115, v78, v79
	v_add_f32_e32 v116, v80, v81
	v_add_f32_e32 v115, v115, v116
	v_add_f32_e32 v114, v114, v115
	v_cvt_pk_bf16_f32 v104, v78, v79
	v_cvt_pk_bf16_f32 v105, v80, v81
	v_add_f32_e32 v200, v200, v114
	s_waitcnt lgkmcnt(4)
	v_mfma_f32_32x32x16_bf16 v[2:17], v[162:165], v[98:101], v[2:17]
	v_exp_f32_e32 v82, v82
	v_exp_f32_e32 v83, v83
	v_exp_f32_e32 v84, v84
	v_exp_f32_e32 v85, v85
	v_mfma_f32_32x32x16_bf16 v[18:33], v[208:211], v[98:101], v[18:33]
	v_add_f32_e32 v114, v82, v83
	v_add_f32_e32 v116, v84, v85
	v_add_f32_e32 v114, v114, v116
	v_cvt_pk_bf16_f32 v106, v82, v83
	v_cvt_pk_bf16_f32 v107, v84, v85
	v_mfma_f32_32x32x16_bf16 v[2:17], v[166:169], v[102:105], v[2:17]
	v_exp_f32_e32 v86, v86
	v_exp_f32_e32 v87, v87
	v_exp_f32_e32 v88, v88
	v_exp_f32_e32 v89, v89
	v_mfma_f32_32x32x16_bf16 v[18:33], v[212:215], v[102:105], v[18:33]
	s_waitcnt lgkmcnt(0)
	v_add_f32_e32 v115, v86, v87
	v_add_f32_e32 v116, v88, v89
	v_add_f32_e32 v115, v115, v116
	v_add_f32_e32 v114, v114, v115
	v_cvt_pk_bf16_f32 v108, v86, v87
	v_cvt_pk_bf16_f32 v109, v88, v89
	v_mfma_f32_32x32x16_bf16 v[66:81], v[146:149], v[130:133], 0
	v_exp_f32_e32 v90, v90
	v_exp_f32_e32 v91, v91
	v_exp_f32_e32 v92, v92
	v_exp_f32_e32 v93, v93
	v_mfma_f32_32x32x16_bf16 v[66:81], v[150:153], v[134:137], v[66:81]
	v_add_f32_e32 v115, v90, v91
	v_add_f32_e32 v116, v92, v93
	v_add_f32_e32 v115, v115, v116
	v_add_f32_e32 v114, v114, v115
	v_cvt_pk_bf16_f32 v110, v90, v91
	v_cvt_pk_bf16_f32 v111, v92, v93
	v_exp_f32_e32 v94, v94
	v_exp_f32_e32 v95, v95
	v_exp_f32_e32 v96, v96
	v_exp_f32_e32 v97, v97
	v_add_f32_e32 v115, v94, v95
	v_add_f32_e32 v116, v96, v97
	v_add_f32_e32 v115, v115, v116
	v_add_f32_e32 v114, v114, v115
	v_cvt_pk_bf16_f32 v112, v94, v95
	v_cvt_pk_bf16_f32 v113, v96, v97
	v_add_f32_e32 v201, v201, v114
	v_mfma_f32_32x32x16_bf16 v[50:65], v[162:165], v[106:109], v[50:65]
	v_exp_f32_e32 v66, v66
	v_exp_f32_e32 v67, v67
	v_exp_f32_e32 v68, v68
	v_exp_f32_e32 v69, v69
	v_mfma_f32_32x32x16_bf16 v[34:49], v[208:211], v[106:109], v[34:49]
	v_add_f32_e32 v114, v66, v67
	v_add_f32_e32 v116, v68, v69
	v_add_f32_e32 v114, v114, v116
	v_cvt_pk_bf16_f32 v98, v66, v67
	v_cvt_pk_bf16_f32 v99, v68, v69
	v_mfma_f32_32x32x16_bf16 v[50:65], v[166:169], v[110:113], v[50:65]
	v_exp_f32_e32 v70, v70
	v_exp_f32_e32 v71, v71
	v_exp_f32_e32 v72, v72
	v_exp_f32_e32 v73, v73
	v_mfma_f32_32x32x16_bf16 v[34:49], v[212:215], v[110:113], v[34:49]
	ds_read_b128 v[162:165], v0 offset:47360
	ds_read_b128 v[166:169], v0 offset:48384
	ds_read_b128 v[208:211], v0 offset:49408
	ds_read_b128 v[212:215], v0 offset:50432
	v_add_f32_e32 v115, v70, v71
	v_add_f32_e32 v116, v72, v73
	v_add_f32_e32 v115, v115, v116
	v_add_f32_e32 v114, v114, v115
	v_cvt_pk_bf16_f32 v100, v70, v71
	v_cvt_pk_bf16_f32 v101, v72, v73
	v_mfma_f32_32x32x16_bf16 v[82:97], v[154:157], v[138:141], 0
	v_exp_f32_e32 v74, v74
	v_exp_f32_e32 v75, v75
	v_exp_f32_e32 v76, v76
	v_exp_f32_e32 v77, v77
	v_mfma_f32_32x32x16_bf16 v[82:97], v[158:161], v[142:145], v[82:97]
	v_add_f32_e32 v115, v74, v75
	v_add_f32_e32 v116, v76, v77
	v_add_f32_e32 v115, v115, v116
	v_add_f32_e32 v114, v114, v115
	v_cvt_pk_bf16_f32 v102, v74, v75
	v_cvt_pk_bf16_f32 v103, v76, v77
	v_exp_f32_e32 v78, v78
	v_exp_f32_e32 v79, v79
	v_exp_f32_e32 v80, v80
	v_exp_f32_e32 v81, v81
	v_add_f32_e32 v115, v78, v79
	v_add_f32_e32 v116, v80, v81
	v_add_f32_e32 v115, v115, v116
	v_add_f32_e32 v114, v114, v115
	v_cvt_pk_bf16_f32 v104, v78, v79
	v_cvt_pk_bf16_f32 v105, v80, v81
	v_add_f32_e32 v200, v200, v114
	s_waitcnt vmcnt(2) lgkmcnt(0)
	s_barrier
; #define LAS __attribute__((address_space(3)))
; __device__ __forceinline__ f32x16 mfma32(bf16x8 a, bf16x8 b, f32x16 c) { return __builtin_amdgcn_mfma_f32_32x32x16_bf16(a, b, c, 0, 0, 0); }
; #define SCHED_FENCE() __builtin_amdgcn_sched_barrier(0)
; #define ISSUE_UP() do { STG_ISSUE(s_iss < sb_end ? s_iss : sb_end, slot_i); ++s_iss; slot_i = slot_i == NSTG - 1 ? 0 : slot_i + 1; } while (0)
; #define EXP4(S_, b_) do { S_[b_] = ex2(S_[b_]); S_[(b_) + 1] = ex2(S_[(b_) + 1]); S_[(b_) + 2] = ex2(S_[(b_) + 2]); S_[(b_) + 3] = ex2(S_[(b_) + 3]); } while (0)
; __device__ __forceinline__ void step_B(const bool FAR, const LAS unsigned char* cb, const LAS unsigned char* tp0, const LAS unsigned char* tp1, const bf16x8 (&qf)[4],
;                                        f32x16& oa0, f32x16& oa1, f32x16& ob0, f32x16& ob1, float& la, float& lb) {
;     ...
;     oa0 = mfma32(vfB[0][0], p0, oa0); EXP4(S3, 0); SCHED_FENCE();
;     oa1 = mfma32(vfB[1][0], p0, oa1); EXP4(S3, 4); SCHED_FENCE();
;     oa0 = mfma32(vfB[0][1], p1, oa0); EXP4(S3, 8); SCHED_FENCE();
;     oa1 = mfma32(vfB[1][1], p1, oa1); EXP4(S3, 12); SCHED_FENCE();
;     SUM16(S3, lb); pack_p(S3, r0, r1); SCHED_FENCE();
;     ob0 = mfma32(vfB[0][0], r0, ob0); ob1 = mfma32(vfB[1][0], r0, ob1); ob0 = mfma32(vfB[0][1], r1, ob0); ob1 = mfma32(vfB[1][1], r1, ob1);
; }
; __device__ __forceinline__ void blk_B(int b, int hd, int chunk, const bf16_t* QK, const bf16_t* VT, bf16_t* mixed, LAS unsigned char* lds, const float* tblg, float wfar, float lam, float osc, const float* subln, int tid, int lane, int wave) {
;     ...
;     for (int sbk = 0; sbk <= sb_end; ++sbk) {
;         ISSUE_UP();
;         const LAS unsigned char* cb = sb + slot_c * STG_BYTES + lane * 16;
;         const int kb0 = 2 * sbk, kb1 = kb0 + 1; const bool c0 = kb0 <= qb, c1 = kb1 <= qb;
;         if (c0 && c1) {
;             const bool far = qb - kb1 >= 49;
;             if (!far && !scaled) { scaled = true;
; #pragma unroll
;                 for (int i = 0; i < 16; ++i) { oa0[i] *= wfar; oa1[i] *= wfar; ob0[i] *= wfar; ob1[i] *= wfar; }
;                 la *= wfar; lb *= wfar; }
;             const int d0 = qb - kb0 < 64 ? qb - kb0 : 64, d1 = qb - kb1 < 64 ? qb - kb1 : 64;
;             step_B(far, cb, tb - d0 * 128, tb - d1 * 128, qf, oa0, oa1, ob0, ob1, la, lb);
	s_add_i32 s0, s77, 1
	s_cmp_lg_u32 s77, 3
	s_cselect_b32 s77, s0, 0
	s_add_i32 s0, s31, 1
	s_cmp_lg_u32 s31, 3
	s_cselect_b32 s31, s0, 0
	s_add_i32 s83, s83, 1
	s_add_i32 s30, s30, -2
	s_add_i32 s79, s79, 2
	v_add_u32_e32 v206, 0x100, v206
	s_cmp_lg_u32 s82, s83
	s_cbranch_scc0 .Lattn_b_fast_exit
	s_add_i32 s0, s83, 0x82
	s_min_u32 s92, s0, s78
	s_lshl_b32 s27, s77, 14
	s_lshl_b64 s[0:1], s[92:93], 18
	v_lshl_add_u64 v[66:67], v[196:197], 0, s[0:1]
	s_add_i32 s0, s76, s27
	v_lshl_add_u64 v[66:67], v[66:67], 0, s[14:15]
	s_add_i32 m0, s0, 0x8900
	s_lshl_b32 s92, s92, 7
	global_load_lds_dwordx4 v[66:67], off
	v_lshl_add_u64 v[66:67], v[198:199], 0, s[92:93]
	s_add_i32 m0, s0, 0x9900
	s_lshl_b32 s27, s31, 14
	global_load_lds_dwordx4 v[66:67], off
	s_cmp_gt_i32 s30, 49
	s_cbranch_scc0 .Lattn_b_fast_to_slow
	v_add_u32_e32 v0, s27, v179
	ds_read_b128 v[146:149], v0 offset:35072
	ds_read_b128 v[150:153], v0 offset:36096
	ds_read_b128 v[154:157], v0 offset:37120
	ds_read_b128 v[158:161], v0 offset:38144
	v_mfma_f32_32x32x16_bf16 v[2:17], v[162:165], v[98:101], v[2:17]
	v_exp_f32_e32 v82, v82
	v_exp_f32_e32 v83, v83
	v_exp_f32_e32 v84, v84
	v_exp_f32_e32 v85, v85
	v_add_f32_e32 v114, v82, v83
	v_add_f32_e32 v116, v84, v85
	v_add_f32_e32 v114, v114, v116
	v_cvt_pk_bf16_f32 v106, v82, v83
	v_cvt_pk_bf16_f32 v107, v84, v85
	v_mfma_f32_32x32x16_bf16 v[18:33], v[208:211], v[98:101], v[18:33]
	v_exp_f32_e32 v86, v86
	v_exp_f32_e32 v87, v87
	v_exp_f32_e32 v88, v88
	v_exp_f32_e32 v89, v89
	v_add_f32_e32 v115, v86, v87
	v_add_f32_e32 v116, v88, v89
	v_add_f32_e32 v115, v115, v116
	v_add_f32_e32 v114, v114, v115
	v_cvt_pk_bf16_f32 v108, v86, v87
	v_cvt_pk_bf16_f32 v109, v88, v89
	v_mfma_f32_32x32x16_bf16 v[2:17], v[166:169], v[102:105], v[2:17]
	v_exp_f32_e32 v90, v90
	v_exp_f32_e32 v91, v91
	v_exp_f32_e32 v92, v92
	v_exp_f32_e32 v93, v93
	v_add_f32_e32 v115, v90, v91
	v_add_f32_e32 v116, v92, v93
	v_add_f32_e32 v115, v115, v116
	v_add_f32_e32 v114, v114, v115
	v_cvt_pk_bf16_f32 v110, v90, v91
	v_cvt_pk_bf16_f32 v111, v92, v93
	v_mfma_f32_32x32x16_bf16 v[18:33], v[212:215], v[102:105], v[18:33]
	v_exp_f32_e32 v94, v94
	v_exp_f32_e32 v95, v95
	v_exp_f32_e32 v96, v96
	v_exp_f32_e32 v97, v97
	v_add_f32_e32 v115, v94, v95
	v_add_f32_e32 v116, v96, v97
	v_add_f32_e32 v115, v115, v116
	v_add_f32_e32 v114, v114, v115
	v_cvt_pk_bf16_f32 v112, v94, v95
	v_cvt_pk_bf16_f32 v113, v96, v97
	v_add_f32_e32 v201, v201, v114
	v_mfma_f32_32x32x16_bf16 v[50:65], v[162:165], v[106:109], v[50:65]
	v_mfma_f32_32x32x16_bf16 v[34:49], v[208:211], v[106:109], v[34:49]
	v_mfma_f32_32x32x16_bf16 v[50:65], v[166:169], v[110:113], v[50:65]
	v_mfma_f32_32x32x16_bf16 v[34:49], v[212:215], v[110:113], v[34:49]
	s_branch .Lattn_b_fast_top

; #define LAS __attribute__((address_space(3)))
; __device__ __forceinline__ f32x16 mfma32(bf16x8 a, bf16x8 b, f32x16 c) { return __builtin_amdgcn_mfma_f32_32x32x16_bf16(a, b, c, 0, 0, 0); }
; #define LOADK(kf_, cb_) do { _Pragma("unroll") for (int s_ = 0; s_ < 4; ++s_) kf_[s_] = *(const LAS bf16x8*)((cb_) + s_ * 1024); } while (0)
; #define LOADV(vf_, cb_) do { _Pragma("unroll") for (int d_ = 0; d_ < 2; ++d_) _Pragma("unroll") for (int s_ = 0; s_ < 2; ++s_) vf_[d_][s_] = *(const LAS bf16x8*)((cb_) + 4096 + (d_ * 2 + s_) * 1024); } while (0)
; #define LOADT(t_, tp_) do { const f32x4 a_ = *(const LAS f32x4*)(tp_), b_ = *(const LAS f32x4*)((tp_) + 16), c_ = *(const LAS f32x4*)((tp_) + 64), d_ = *(const LAS f32x4*)((tp_) + 80); \
;     t_ = (f32x16){a_[0], a_[1], a_[2], a_[3], b_[0], b_[1], b_[2], b_[3], c_[0], c_[1], c_[2], c_[3], d_[0], d_[1], d_[2], d_[3]}; } while (0)
; #define SCHED_FENCE() __builtin_amdgcn_sched_barrier(0)
; #define EXP4(S_, b_) do { S_[b_] = ex2(S_[b_]); S_[(b_) + 1] = ex2(S_[(b_) + 1]); S_[(b_) + 2] = ex2(S_[(b_) + 2]); S_[(b_) + 3] = ex2(S_[(b_) + 3]); } while (0)
; __device__ __forceinline__ void step_B(const bool FAR, const LAS unsigned char* cb, const LAS unsigned char* tp0, const LAS unsigned char* tp1, const bf16x8 (&qf)[4],
;                                        f32x16& oa0, f32x16& oa1, f32x16& ob0, f32x16& ob1, float& la, float& lb) {
;     bf16x8 kfA[4], vfA[2][2], kfB[4], vfB[2][2]; f32x16 tA, tB;
;     LOADK(kfA, cb); if (!FAR) LOADT(tA, tp0); LOADV(vfA, cb);
;     SCHED_FENCE();
;     f32x16 S0, S1;
;     if (FAR) { S0 = mfma32(kfA[0], qf[0], f32x16{}); S1 = mfma32(kfA[2], qf[2], f32x16{}); }
;     else { S0 = mfma32(kfA[0], qf[0], tA); S1 = mfma32(kfA[2], qf[2], tA); }
;     S0 = mfma32(kfA[1], qf[1], S0); S1 = mfma32(kfA[3], qf[3], S1);
;     kfB[0] = *(const LAS bf16x8*)(cb + 8192); kfB[1] = *(const LAS bf16x8*)(cb + 8192 + 1024); if (!FAR) LOADT(tB, tp1);
;     SCHED_FENCE();
;     bf16x8 p0, p1, r0, r1;
;     f32x16 S2; if (FAR) S2 = mfma32(kfB[0], qf[0], f32x16{}); else S2 = mfma32(kfB[0], qf[0], tB);
;     EXP4(S0, 0); EXP4(S0, 4); SCHED_FENCE();
;     S2 = mfma32(kfB[1], qf[1], S2); EXP4(S0, 8); EXP4(S0, 12); SCHED_FENCE();
.Lattn_b_lag_entry:
	v_add_u32_e32 v0, s27, v179
	ds_read_b128 v[146:149], v0 offset:35072
	ds_read_b128 v[150:153], v0 offset:36096
	ds_read_b128 v[154:157], v0 offset:37120
	ds_read_b128 v[158:161], v0 offset:38144
.Lattn_b_lag_top:
	s_waitcnt lgkmcnt(0)
	v_mfma_f32_32x32x16_bf16 v[66:81], v[146:149], v[130:133], 0
	v_mfma_f32_32x32x16_bf16 v[66:81], v[150:153], v[134:137], v[66:81]
	ds_read_b128 v[162:165], v0 offset:39168
	ds_read_b128 v[166:169], v0 offset:40192
	ds_read_b128 v[208:211], v0 offset:41216
	ds_read_b128 v[212:215], v0 offset:42240
	ds_read_b128 v[146:149], v0 offset:43264
	ds_read_b128 v[150:153], v0 offset:44288
	s_nop 4
	v_mfma_f32_32x32x16_bf16 v[82:97], v[154:157], v[138:141], 0
	v_exp_f32_e32 v66, v66
	v_exp_f32_e32 v67, v67
	v_exp_f32_e32 v68, v68
	v_exp_f32_e32 v69, v69
	v_add_f32_e32 v114, v66, v67
	v_add_f32_e32 v116, v68, v69
	v_add_f32_e32 v114, v114, v116
	v_cvt_pk_bf16_f32 v98, v66, v67
	v_cvt_pk_bf16_f32 v99, v68, v69
	v_mfma_f32_32x32x16_bf16 v[82:97], v[158:161], v[142:145], v[82:97]
	ds_read_b128 v[154:157], v0 offset:45312
	ds_read_b128 v[158:161], v0 offset:46336
	v_exp_f32_e32 v70, v70
	v_exp_f32_e32 v71, v71
	v_exp_f32_e32 v72, v72
	v_exp_f32_e32 v73, v73
	v_add_f32_e32 v115, v70, v71
	v_add_f32_e32 v116, v72, v73
	v_add_f32_e32 v115, v115, v116
	v_add_f32_e32 v114, v114, v115
	v_cvt_pk_bf16_f32 v100, v70, v71
	v_cvt_pk_bf16_f32 v101, v72, v73
	v_exp_f32_e32 v74, v74
	v_exp_f32_e32 v75, v75
	v_exp_f32_e32 v76, v76
	v_exp_f32_e32 v77, v77
	v_add_f32_e32 v115, v74, v75
	v_add_f32_e32 v116, v76, v77
	v_add_f32_e32 v115, v115, v116
	v_add_f32_e32 v114, v114, v115
	v_cvt_pk_bf16_f32 v102, v74, v75
	v_cvt_pk_bf16_f32 v103, v76, v77
	v_exp_f32_e32 v78, v78
	v_exp_f32_e32 v79, v79
	v_exp_f32_e32 v80, v80
	v_exp_f32_e32 v81, v81
	v_add_f32_e32 v115, v78, v79
	v_add_f32_e32 v116, v80, v81
	v_add_f32_e32 v115, v115, v116
	v_add_f32_e32 v114, v114, v115
	v_cvt_pk_bf16_f32 v104, v78, v79
	v_cvt_pk_bf16_f32 v105, v80, v81
	v_add_f32_e32 v200, v200, v114
	s_waitcnt vmcnt(2)
	s_barrier
; #define LAS __attribute__((address_space(3)))
; __device__ __forceinline__ f32x16 mfma32(bf16x8 a, bf16x8 b, f32x16 c) { return __builtin_amdgcn_mfma_f32_32x32x16_bf16(a, b, c, 0, 0, 0); }
; __device__ __forceinline__ void step_B(const bool FAR, const LAS unsigned char* cb, const LAS unsigned char* tp0, const LAS unsigned char* tp1, const bf16x8 (&qf)[4],
;                                        f32x16& oa0, f32x16& oa1, f32x16& ob0, f32x16& ob1, float& la, float& lb) {
;     ...
;     S2 = mfma32(kfB[1], qf[1], S2); EXP4(S0, 8); EXP4(S0, 12); SCHED_FENCE();
;     SUM16(S0, la); pack_p(S0, p0, p1); SCHED_FENCE();
;     f32x16 tB2; kfB[2] = *(const LAS bf16x8*)(cb + 8192 + 2048); kfB[3] = *(const LAS bf16x8*)(cb + 8192 + 3072); if (!FAR) LOADT(tB2, tp1);
;     oa0 = mfma32(vfA[0][0], p0, oa0); EXP4(S1, 0); SCHED_FENCE();
;     oa1 = mfma32(vfA[1][0], p0, oa1); EXP4(S1, 4); SCHED_FENCE();
;     oa0 = mfma32(vfA[0][1], p1, oa0); EXP4(S1, 8); SCHED_FENCE();
;     oa1 = mfma32(vfA[1][1], p1, oa1); EXP4(S1, 12); SCHED_FENCE();
;     f32x16 S3; if (FAR) S3 = mfma32(kfB[2], qf[2], f32x16{}); else S3 = mfma32(kfB[2], qf[2], tB2);
;     SUM16(S1, lb); SCHED_FENCE();
;     S3 = mfma32(kfB[3], qf[3], S3); pack_p(S1, r0, r1); SCHED_FENCE();
;     LOADV(vfB, cb + 8192);
;     ob0 = mfma32(vfA[0][0], r0, ob0); EXP4(S2, 0); SCHED_FENCE();
;     ob1 = mfma32(vfA[1][0], r0, ob1); EXP4(S2, 4); SCHED_FENCE();
;     ob0 = mfma32(vfA[0][1], r1, ob0); EXP4(S2, 8); SCHED_FENCE();
;     ob1 = mfma32(vfA[1][1], r1, ob1); EXP4(S2, 12); SCHED_FENCE();
;     SUM16(S2, la); pack_p(S2, p0, p1); SCHED_FENCE();
;     oa0 = mfma32(vfB[0][0], p0, oa0); EXP4(S3, 0); SCHED_FENCE();
;     oa1 = mfma32(vfB[1][0], p0, oa1); EXP4(S3, 4); SCHED_FENCE();
;     oa0 = mfma32(vfB[0][1], p1, oa0); EXP4(S3, 8); SCHED_FENCE();
;     oa1 = mfma32(vfB[1][1], p1, oa1); EXP4(S3, 12); SCHED_FENCE();
;     SUM16(S3, lb); pack_p(S3, r0, r1); SCHED_FENCE();
;     ob0 = mfma32(vfB[0][0], r0, ob0); ob1 = mfma32(vfB[1][0], r0, ob1); ob0 = mfma32(vfB[0][1], r1, ob0); ob1 = mfma32(vfB[1][1], r1, ob1);
; }
; __device__ __forceinline__ void blk_B(int b, int hd, int chunk, const bf16_t* QK, const bf16_t* VT, bf16_t* mixed, LAS unsigned char* lds, const float* tblg, float wfar, float lam, float osc, const float* subln, int tid, int lane, int wave) {
;     ...
;         WAITBAR2();
;         slot_c = slot_c == NSTG - 1 ? 0 : slot_c + 1;
	s_add_i32 s0, s77, 1
	s_cmp_lg_u32 s77, 3
	s_cselect_b32 s77, s0, 0
	s_add_i32 s83, s83, 1
	s_add_i32 s0, s83, 0x82
	s_min_u32 s92, s0, s78
	s_lshl_b32 s27, s77, 14
	s_lshl_b64 s[0:1], s[92:93], 18
	v_lshl_add_u64 v[66:67], v[196:197], 0, s[0:1]
	s_add_i32 s0, s76, s27
	v_lshl_add_u64 v[66:67], v[66:67], 0, s[14:15]
	s_add_i32 m0, s0, 0x8900
	s_lshl_b32 s92, s92, 7
	global_load_lds_dwordx4 v[66:67], off
	v_lshl_add_u64 v[66:67], v[198:199], 0, s[92:93]
	s_add_i32 m0, s0, 0x9900
	s_nop 0
	global_load_lds_dwordx4 v[66:67], off
	s_waitcnt lgkmcnt(4)
	v_mfma_f32_32x32x16_bf16 v[2:17], v[162:165], v[98:101], v[2:17]
	v_exp_f32_e32 v82, v82
	v_exp_f32_e32 v83, v83
	v_exp_f32_e32 v84, v84
	v_exp_f32_e32 v85, v85
	v_mfma_f32_32x32x16_bf16 v[18:33], v[208:211], v[98:101], v[18:33]
	v_add_f32_e32 v114, v82, v83
	v_add_f32_e32 v116, v84, v85
	v_add_f32_e32 v114, v114, v116
	v_cvt_pk_bf16_f32 v106, v82, v83
	v_cvt_pk_bf16_f32 v107, v84, v85
	v_mfma_f32_32x32x16_bf16 v[2:17], v[166:169], v[102:105], v[2:17]
	v_exp_f32_e32 v86, v86
	v_exp_f32_e32 v87, v87
	v_exp_f32_e32 v88, v88
	v_exp_f32_e32 v89, v89
	v_mfma_f32_32x32x16_bf16 v[18:33], v[212:215], v[102:105], v[18:33]
	s_waitcnt lgkmcnt(0)
	v_add_f32_e32 v115, v86, v87
	v_add_f32_e32 v116, v88, v89
	v_add_f32_e32 v115, v115, v116
	v_add_f32_e32 v114, v114, v115
	v_cvt_pk_bf16_f32 v108, v86, v87
	v_cvt_pk_bf16_f32 v109, v88, v89
	v_mfma_f32_32x32x16_bf16 v[66:81], v[146:149], v[130:133], 0
	v_exp_f32_e32 v90, v90
	v_exp_f32_e32 v91, v91
	v_exp_f32_e32 v92, v92
	v_exp_f32_e32 v93, v93
	v_mfma_f32_32x32x16_bf16 v[66:81], v[150:153], v[134:137], v[66:81]
	v_add_f32_e32 v115, v90, v91
	v_add_f32_e32 v116, v92, v93
	v_add_f32_e32 v115, v115, v116
	v_add_f32_e32 v114, v114, v115
	v_cvt_pk_bf16_f32 v110, v90, v91
	v_cvt_pk_bf16_f32 v111, v92, v93
	v_exp_f32_e32 v94, v94
	v_exp_f32_e32 v95, v95
	v_exp_f32_e32 v96, v96
	v_exp_f32_e32 v97, v97
	v_add_f32_e32 v115, v94, v95
	v_add_f32_e32 v116, v96, v97
	v_add_f32_e32 v115, v115, v116
	v_add_f32_e32 v114, v114, v115
	v_cvt_pk_bf16_f32 v112, v94, v95
	v_cvt_pk_bf16_f32 v113, v96, v97
	v_add_f32_e32 v201, v201, v114
	v_mfma_f32_32x32x16_bf16 v[50:65], v[162:165], v[106:109], v[50:65]
	v_exp_f32_e32 v66, v66
	v_exp_f32_e32 v67, v67
	v_exp_f32_e32 v68, v68
	v_exp_f32_e32 v69, v69
	v_mfma_f32_32x32x16_bf16 v[34:49], v[208:211], v[106:109], v[34:49]
	v_add_f32_e32 v114, v66, v67
	v_add_f32_e32 v116, v68, v69
	v_add_f32_e32 v114, v114, v116
	v_cvt_pk_bf16_f32 v98, v66, v67
	v_cvt_pk_bf16_f32 v99, v68, v69
	v_mfma_f32_32x32x16_bf16 v[50:65], v[166:169], v[110:113], v[50:65]
	v_exp_f32_e32 v70, v70
	v_exp_f32_e32 v71, v71
	v_exp_f32_e32 v72, v72
	v_exp_f32_e32 v73, v73
	v_mfma_f32_32x32x16_bf16 v[34:49], v[212:215], v[110:113], v[34:49]
	ds_read_b128 v[162:165], v0 offset:47360
	ds_read_b128 v[166:169], v0 offset:48384
	ds_read_b128 v[208:211], v0 offset:49408
	ds_read_b128 v[212:215], v0 offset:50432
	v_add_f32_e32 v115, v70, v71
	v_add_f32_e32 v116, v72, v73
	v_add_f32_e32 v115, v115, v116
	v_add_f32_e32 v114, v114, v115
	v_cvt_pk_bf16_f32 v100, v70, v71
	v_cvt_pk_bf16_f32 v101, v72, v73
	v_mfma_f32_32x32x16_bf16 v[82:97], v[154:157], v[138:141], 0
	v_exp_f32_e32 v74, v74
	v_exp_f32_e32 v75, v75
	v_exp_f32_e32 v76, v76
	v_exp_f32_e32 v77, v77
	v_mfma_f32_32x32x16_bf16 v[82:97], v[158:161], v[142:145], v[82:97]
	v_add_f32_e32 v115, v74, v75
	v_add_f32_e32 v116, v76, v77
	v_add_f32_e32 v115, v115, v116
	v_add_f32_e32 v114, v114, v115
	v_cvt_pk_bf16_f32 v102, v74, v75
	v_cvt_pk_bf16_f32 v103, v76, v77
	v_exp_f32_e32 v78, v78
	v_exp_f32_e32 v79, v79
	v_exp_f32_e32 v80, v80
	v_exp_f32_e32 v81, v81
	v_add_f32_e32 v115, v78, v79
	v_add_f32_e32 v116, v80, v81
	v_add_f32_e32 v115, v115, v116
	v_add_f32_e32 v114, v114, v115
	v_cvt_pk_bf16_f32 v104, v78, v79
	v_cvt_pk_bf16_f32 v105, v80, v81
	v_add_f32_e32 v200, v200, v114
	s_waitcnt lgkmcnt(0)
	s_add_i32 s0, s31, 1
	s_cmp_lg_u32 s31, 3
	s_cselect_b32 s31, s0, 0
	s_add_i32 s30, s30, -2
	s_add_i32 s79, s79, 2
	v_add_u32_e32 v206, 0x100, v206
	s_cmp_lg_u32 s82, s83
	s_cbranch_scc0 .Lattn_b_lag_exit
	s_lshl_b32 s27, s31, 14
	s_cmp_gt_i32 s30, 49
	s_cbranch_scc0 .Lattn_b_lag_to_slow
	v_add_u32_e32 v0, s27, v179
	ds_read_b128 v[146:149], v0 offset:35072
	ds_read_b128 v[150:153], v0 offset:36096
	ds_read_b128 v[154:157], v0 offset:37120
	ds_read_b128 v[158:161], v0 offset:38144
	v_mfma_f32_32x32x16_bf16 v[2:17], v[162:165], v[98:101], v[2:17]
	v_exp_f32_e32 v82, v82
	v_exp_f32_e32 v83, v83
	v_exp_f32_e32 v84, v84
	v_exp_f32_e32 v85, v85
	v_add_f32_e32 v114, v82, v83
	v_add_f32_e32 v116, v84, v85
	v_add_f32_e32 v114, v114, v116
	v_cvt_pk_bf16_f32 v106, v82, v83
	v_cvt_pk_bf16_f32 v107, v84, v85
	v_mfma_f32_32x32x16_bf16 v[18:33], v[208:211], v[98:101], v[18:33]
	v_exp_f32_e32 v86, v86
	v_exp_f32_e32 v87, v87
	v_exp_f32_e32 v88, v88
	v_exp_f32_e32 v89, v89
	v_add_f32_e32 v115, v86, v87
	v_add_f32_e32 v116, v88, v89
	v_add_f32_e32 v115, v115, v116
	v_add_f32_e32 v114, v114, v115
	v_cvt_pk_bf16_f32 v108, v86, v87
	v_cvt_pk_bf16_f32 v109, v88, v89
	v_mfma_f32_32x32x16_bf16 v[2:17], v[166:169], v[102:105], v[2:17]
	v_exp_f32_e32 v90, v90
	v_exp_f32_e32 v91, v91
	v_exp_f32_e32 v92, v92
	v_exp_f32_e32 v93, v93
	v_add_f32_e32 v115, v90, v91
	v_add_f32_e32 v116, v92, v93
	v_add_f32_e32 v115, v115, v116
	v_add_f32_e32 v114, v114, v115
	v_cvt_pk_bf16_f32 v110, v90, v91
	v_cvt_pk_bf16_f32 v111, v92, v93
	v_mfma_f32_32x32x16_bf16 v[18:33], v[212:215], v[102:105], v[18:33]
	v_exp_f32_e32 v94, v94
	v_exp_f32_e32 v95, v95
	v_exp_f32_e32 v96, v96
	v_exp_f32_e32 v97, v97
	v_add_f32_e32 v115, v94, v95
	v_add_f32_e32 v116, v96, v97
	v_add_f32_e32 v115, v115, v116
	v_add_f32_e32 v114, v114, v115
	v_cvt_pk_bf16_f32 v112, v94, v95
	v_cvt_pk_bf16_f32 v113, v96, v97
	v_add_f32_e32 v201, v201, v114
	v_mfma_f32_32x32x16_bf16 v[50:65], v[162:165], v[106:109], v[50:65]
	v_mfma_f32_32x32x16_bf16 v[34:49], v[208:211], v[106:109], v[34:49]
	v_mfma_f32_32x32x16_bf16 v[50:65], v[166:169], v[110:113], v[50:65]
	v_mfma_f32_32x32x16_bf16 v[34:49], v[212:215], v[110:113], v[34:49]
	s_branch .Lattn_b_lag_top
